# grid barrier: waiting workgroups poll the cross-XCD release word directly (one hop less), on top of the early-invalidate version
# baseline (speedup 1.0000x reference)
; __device__ __forceinline__ unsigned xb_ld(unsigned* p)              { return __hip_atomic_load(p, __ATOMIC_RELAXED, __HIP_MEMORY_SCOPE_AGENT); }
; #define XB_SPIN(cond, bar) do { unsigned _sp = 0; while (cond) { __builtin_amdgcn_s_sleep(1); \
;     if ((++_sp & 255u) == 0u) { if (xb_ld(&(bar)[XB_TMO])) break; if (_sp > XB_SPIN_CAP) { atomicAdd(&(bar)[XB_TMO], 1u); break; } } } } while (0)
; __device__ __forceinline__ void xcd_barrier(const XcdBarrier& b) {
;     ...
;         } else {
;             XB_SPIN(xb_ld(&bar[XB_XGEN(b.x)]) == gen, bar);
;             __builtin_amdgcn_fence(__ATOMIC_ACQUIRE, "agent");
.LBB0_253:
	s_or_b64 exec, exec, s[6:7]
	v_cvt_f32_u32_e32 v5, v3
	s_waitcnt vmcnt(0)
	v_readfirstlane_b32 s6, v4
	v_sub_u32_e32 v4, 0, v3
	v_rcp_iflag_f32_e32 v5, v5
	v_add_u32_e32 v6, s6, v0
	v_mul_f32_e32 v5, 0x4f7ffffe, v5
	v_cvt_u32_f32_e32 v5, v5
	v_mul_lo_u32 v0, v4, v5
	v_mul_hi_u32 v0, v5, v0
	v_add_u32_e32 v0, v5, v0
	v_mul_hi_u32 v0, v6, v0
	v_mul_lo_u32 v4, v0, v3
	v_sub_u32_e32 v4, v6, v4
	v_add_u32_e32 v5, 1, v0
	v_cmp_ge_u32_e32 vcc, v4, v3
	s_nop 1
	v_cndmask_b32_e32 v0, v0, v5, vcc
	v_sub_u32_e32 v5, v4, v3
	v_cndmask_b32_e32 v4, v4, v5, vcc
	v_add_u32_e32 v5, 1, v0
	v_cmp_ge_u32_e32 vcc, v4, v3
	v_add_u32_e32 v4, 1, v6
	s_nop 0
	v_cndmask_b32_e32 v0, v0, v5, vcc
	v_mul_lo_u32 v5, v3, v0
	v_add_u32_e32 v3, v5, v3
	v_cmp_ne_u32_e32 vcc, v4, v3
	s_and_saveexec_b64 s[6:7], vcc
	s_xor_b64 s[6:7], exec, s[6:7]
	s_cbranch_execz .LBB0_267
	v_readlane_b32 s8, v253, 13
	v_readlane_b32 s9, v253, 14
	s_waitcnt lgkmcnt(0)
	s_nop 3
	buffer_inv sc1
	global_load_dword v2, v1, s[8:9] sc1
	s_waitcnt vmcnt(0)
	v_cmp_eq_u32_e32 vcc, v2, v0
	s_and_saveexec_b64 s[8:9], vcc
	s_cbranch_execz .LBB0_266
	s_mov_b32 s20, 1
	s_mov_b64 s[10:11], 0
	s_branch .LBB0_257

; __device__ __forceinline__ unsigned xb_ld(unsigned* p)              { return __hip_atomic_load(p, __ATOMIC_RELAXED, __HIP_MEMORY_SCOPE_AGENT); }
; #define XB_SPIN(cond, bar) do { unsigned _sp = 0; while (cond) { __builtin_amdgcn_s_sleep(1); \
;     if ((++_sp & 255u) == 0u) { if (xb_ld(&(bar)[XB_TMO])) break; if (_sp > XB_SPIN_CAP) { atomicAdd(&(bar)[XB_TMO], 1u); break; } } } } while (0)
; __device__ __forceinline__ void xcd_barrier(const XcdBarrier& b) {
;     ...
;         } else {
;             XB_SPIN(xb_ld(&bar[XB_XGEN(b.x)]) == gen, bar);
;             __builtin_amdgcn_fence(__ATOMIC_ACQUIRE, "agent");
.LBB0_1593:
	s_or_b64 exec, exec, s[8:9]
	v_cvt_f32_u32_e32 v5, v3
	s_waitcnt vmcnt(0)
	v_readfirstlane_b32 s8, v4
	v_sub_u32_e32 v4, 0, v3
	v_rcp_iflag_f32_e32 v5, v5
	v_add_u32_e32 v6, s8, v0
	v_mul_f32_e32 v5, 0x4f7ffffe, v5
	v_cvt_u32_f32_e32 v5, v5
	v_mul_lo_u32 v0, v4, v5
	v_mul_hi_u32 v0, v5, v0
	v_add_u32_e32 v0, v5, v0
	v_mul_hi_u32 v0, v6, v0
	v_mul_lo_u32 v4, v0, v3
	v_sub_u32_e32 v4, v6, v4
	v_add_u32_e32 v5, 1, v0
	v_cmp_ge_u32_e32 vcc, v4, v3
	s_nop 1
	v_cndmask_b32_e32 v0, v0, v5, vcc
	v_sub_u32_e32 v5, v4, v3
	v_cndmask_b32_e32 v4, v4, v5, vcc
	v_add_u32_e32 v5, 1, v0
	v_cmp_ge_u32_e32 vcc, v4, v3
	v_add_u32_e32 v4, 1, v6
	s_nop 0
	v_cndmask_b32_e32 v0, v0, v5, vcc
	v_mul_lo_u32 v5, v3, v0
	v_add_u32_e32 v3, v5, v3
	v_cmp_ne_u32_e32 vcc, v4, v3
	s_and_saveexec_b64 s[8:9], vcc
	s_xor_b64 s[8:9], exec, s[8:9]
	s_cbranch_execz .LBB0_1607
	v_readlane_b32 s10, v253, 13
	v_readlane_b32 s11, v253, 14
	s_waitcnt lgkmcnt(0)
	s_nop 3
	buffer_inv sc1
	global_load_dword v2, v1, s[10:11] sc1
	s_waitcnt vmcnt(0)
	v_cmp_eq_u32_e32 vcc, v2, v0
	s_and_saveexec_b64 s[10:11], vcc
	s_cbranch_execz .LBB0_1606
	s_mov_b32 s22, 1
	s_mov_b64 s[12:13], 0
	s_branch .LBB0_1597
